# loop-edge edit: first K-tile LDS reads of the next QK^T segment hoisted ahead of the inter-segment VALU and the loop back-edge in the GQA loop
# baseline (speedup 1.0000x reference)
; __device__ __forceinline__ int v_st(int k, int c) { const int kk = (k & ~0xC) | ((k & 4) << 1) | ((k & 8) >> 1); return ((kk >> 3) * 4 + (c >> 5)) * 512 + ((kk & 7) * 32 + (c & 31)) * 2; }
; __device__ __forceinline__ int v_rd_base(int lane) { return ((lane & 3) << 3) | (((lane >> 2) & 3) << 6) | (((lane >> 4) & 1) << 5) | (((lane >> 5) & 1) << 8); }
; #define SLOAD(i, k0) do { sr_[i].vs0 = *reinterpret_cast<const bf16x8*>(vptr + (size_t)((k0) + sr) * vstr); \
;     sr_[i].vs1 = *reinterpret_cast<const bf16x8*>(vptr + (size_t)((k0) + 32 + sr) * vstr); \
;     sr_[i].ks0 = *reinterpret_cast<const bf16x8*>(kptr + (size_t)((k0) + sr) * kstr); \
;     sr_[i].ks1 = *reinterpret_cast<const bf16x8*>(kptr + (size_t)((k0) + 32 + sr) * kstr); } while (0)
; template <int NDQ, int NDV> ...
;     ...
;   const bf16_t* Qw = Qb + (size_t)(wid * 32 + r32) * ldq + hi * 8;
; #pragma unroll
;   for (int d0 = 0; d0 < NDQ; ++d0) qr[d0] = *reinterpret_cast<const bf16x8*>(Qw + d0 * 16);
;   const int sr = tid >> 4, sc = (tid & 15) * 8, vst0 = v_st(sr, sc), vst1 = v_st(32 + sr, sc);
;   const int vb0 = (int)(unsigned)(size_t)V_lds + v_rd_base(lane);
;   struct { bf16x8 vs0, vs1, ks0, ks1; } sr_[2];
;     ...
;   f32x16 pA0, pA1, pB0, pB1; float mnA, mnB, alA, alB; bf16x8 pa0, pa1, pa2, pa3; const int NT = seq / 64;
;   constexpr int SE = 0, SO = 1;
;   __syncthreads();
;   SLOAD(SE, 0); asm volatile("s_waitcnt vmcnt(0)" ::: "memory"); SWRITE(0, SE); __syncthreads();
;   qkt<NDQ>(pA0, pA1, K_lds, qr, r32, hi); partialSM(pA0, pA1, m_reg, mnA, alA, Cs, thr);
; __device__ __forceinline__ void phase_mix1(const Params& p, LP lds) {
;     ...
;   for (int t = blockIdx.x; t < 1024; t += gridDim.x) {
;     const int blkv = t & 255, rnd = t >> 8, bh = rnd * 8 + (blkv & 7), qb = blkv >> 3, b = bh >> 3, h = bh & 7, kvh = h >> 2;
;     const int row0 = b * TPB + CTXL + qb * 256;
;     const size_t kb = (size_t)b * TPB;
;     attn_body<8, 4>(Q + (size_t)row0 * 1536 + h * 128, 1536, Q + kb * 1536 + 1024 + kvh * 128 + sc, 1536, Q + kb * 1536 + 1280 + kvh * 128 + sc, 1536,
.LBB0_2122:
	s_ashr_i32 s3, s59, 8
	s_lshl_b32 s28, s59, 5
	s_mul_i32 s1, s3, 0x2100
	s_and_b32 s28, s28, 0x1f00
	s_add_i32 s1, s1, s28
	s_add_i32 s28, s1, 0x100
	s_and_b32 s2, s58, 4
	s_and_b32 s0, s59, 7
	s_ashr_i32 s29, s28, 31
	s_mul_i32 s30, s28, 0xc00
	s_mul_hi_i32 s1, s28, 0xc00
	s_add_u32 s30, s5, s30
	s_addc_u32 s1, s35, s1
	s_lshl_b32 s60, s0, 7
	s_lshl_b32 s0, s0, 8
	s_add_u32 s0, s30, s0
	s_addc_u32 s1, s1, 0
	s_mul_i32 s31, s3, 0x18c0000
	s_mul_hi_i32 s30, s3, 0x18c0000
	s_add_u32 s31, s5, s31
	s_addc_u32 s36, s35, s30
	s_lshl_b32 s30, s59, 6
	s_and_b32 s30, s30, 0x100
	v_mov_b32_e32 v58, v190
	s_add_u32 s30, s31, s30
	s_addc_u32 s31, s36, 0
	v_ashrrev_i32_e32 v59, 1, v58
	v_bfe_u32 v188, v58, 5, 1
	v_bfi_b32 v2, s41, v59, v58
	v_mov_b64_e32 v[0:1], s[0:1]
	v_ashrrev_i32_e32 v70, 4, v58
	v_lshl_add_u64 v[48:49], s[30:31], 0, v[180:181]
	v_mad_i64_i32 v[0:1], s[0:1], v2, s40, v[0:1]
	v_lshlrev_b32_e32 v176, 4, v188
	v_add_u32_e32 v16, 32, v70
	v_lshl_add_u64 v[0:1], v[0:1], 0, v[176:177]
	v_mad_i64_i32 v[8:9], s[0:1], v70, s40, v[48:49]
	v_mad_i64_i32 v[12:13], s[0:1], v16, s40, v[48:49]
	global_load_dwordx4 v[124:127], v[0:1], off
	global_load_dwordx4 v[120:123], v[0:1], off offset:32
	global_load_dwordx4 v[116:119], v[0:1], off offset:64
	global_load_dwordx4 v[112:115], v[0:1], off offset:96
	global_load_dwordx4 v[108:111], v[0:1], off offset:128
	global_load_dwordx4 v[104:107], v[0:1], off offset:160
	global_load_dwordx4 v[100:103], v[0:1], off offset:192
	global_load_dwordx4 v[96:99], v[0:1], off offset:224
	s_barrier
	global_load_dwordx4 v[0:3], v[8:9], off offset:2560
	global_load_dwordx4 v[4:7], v[12:13], off offset:2560
	s_nop 0
	global_load_dwordx4 v[8:11], v[8:9], off offset:2048
	s_nop 0
	global_load_dwordx4 v[12:15], v[12:13], off offset:2048
	v_lshlrev_b32_e32 v17, 3, v58
	v_and_b32_e32 v20, 0xfffff0, v70
	v_lshlrev_b32_e32 v21, 1, v70
	v_lshrrev_b32_e32 v22, 1, v70
	v_and_b32_e32 v23, 3, v70
	v_and_b32_e32 v19, 0x78, v17
	v_and_or_b32 v20, v21, 8, v20
	v_and_or_b32 v21, v22, 4, v23
	v_and_b32_e32 v22, 0xfffff0, v16
	v_lshlrev_b32_e32 v23, 1, v16
	v_and_b32_e32 v18, 0xf0, v58
	v_bfe_u32 v17, v17, 5, 2
	v_lshlrev_b32_e32 v24, 8, v70
	v_lshlrev_b32_e32 v19, 1, v19
	v_lshlrev_b32_e32 v16, 8, v16
	v_lshrrev_b32_e32 v20, 1, v20
	v_and_or_b32 v22, v23, 8, v22
	v_and_b32_e32 v25, 48, v19
	v_bitop3_b32 v23, v19, v24, v18 bitop3:0xde
	v_bitop3_b32 v16, v19, v16, v18 bitop3:0xde
	v_or_b32_e32 v18, v20, v17
	v_lshrrev_b32_e32 v19, 1, v22
	v_lshlrev_b32_e32 v21, 6, v21
	v_add_u32_e32 v196, 0, v16
	v_lshlrev_b32_e32 v16, 9, v18
	v_or_b32_e32 v17, v19, v17
	v_or3_b32 v16, v16, v21, v25
	v_lshlrev_b32_e32 v17, 9, v17
	v_and_b32_e32 v189, 31, v58
	v_lshlrev_b32_e32 v60, 4, v58
	v_or3_b32 v17, v17, v21, v25
	v_add_u32_e32 v197, 0, v16
	v_add_u32_e32 v195, 0, v23
	v_add_u32_e32 v198, 0, v17
	s_waitcnt vmcnt(0)
	v_lshl_add_u32 v61, v189, 8, 0
	v_and_b32_e32 v62, 0xf0, v60
	v_and_b32_e32 v71, 63, v58
	v_and_b32_e32 v63, 0x3fffffc0, v58
	v_lshlrev_b32_e32 v58, 1, v58
	v_and_b32_e32 v182, 0xffffffe0, v59
	v_lshlrev_b32_e32 v59, 3, v71
	v_and_b32_e32 v58, 32, v58
	v_lshl_add_u32 v183, v63, 2, s74
	v_mad_i64_i32 v[66:67], s[0:1], v70, s40, 0
	v_lshl_add_u32 v191, v189, 2, v183
	s_mov_b32 s61, -1
	s_waitcnt vmcnt(3)
	ds_write_b128 v197, v[0:3]
	s_waitcnt vmcnt(2)
	ds_write_b128 v198, v[4:7]
	s_waitcnt vmcnt(1)
	ds_write_b128 v195, v[8:11] offset:32768
	s_waitcnt vmcnt(0)
	ds_write_b128 v196, v[12:15] offset:32768
	v_bitop3_b32 v0, v176, v60, s43 bitop3:0x78
	v_add_u32_e32 v199, v61, v0
	s_waitcnt lgkmcnt(0)
	s_barrier
	ds_read_b128 v[0:3], v199 offset:32768
	ds_read_b128 v[4:7], v199 offset:40960
	s_waitcnt lgkmcnt(1)
	v_mfma_f32_32x32x16_bf16 v[32:47], v[0:3], v[124:127], 0
	v_bitop3_b32 v0, v176, v62, 32 bitop3:0x36
	v_add_u32_e32 v200, v61, v0
	v_and_b32_e32 v60, 0xc0, v60
	v_mov_b32_e32 v192, 0
	s_waitcnt lgkmcnt(0)
	v_mfma_f32_32x32x16_bf16 v[16:31], v[4:7], v[124:127], 0
	ds_read_b128 v[0:3], v200 offset:32768
	ds_read_b128 v[4:7], v200 offset:40960
	s_waitcnt lgkmcnt(1)
	v_mfma_f32_32x32x16_bf16 v[32:47], v[0:3], v[120:123], v[32:47]
	v_bitop3_b32 v0, v176, v62, 64 bitop3:0x36
	v_add_u32_e32 v201, v61, v0
	s_waitcnt lgkmcnt(0)
	v_mfma_f32_32x32x16_bf16 v[16:31], v[4:7], v[120:123], v[16:31]
	ds_read_b128 v[0:3], v201 offset:32768
	ds_read_b128 v[4:7], v201 offset:40960
	s_waitcnt lgkmcnt(1)
	v_mfma_f32_32x32x16_bf16 v[32:47], v[0:3], v[116:119], v[32:47]
	v_bitop3_b32 v0, v176, v62, s44 bitop3:0x36
	v_add_u32_e32 v202, v61, v0
	s_waitcnt lgkmcnt(0)
	v_mfma_f32_32x32x16_bf16 v[16:31], v[4:7], v[116:119], v[16:31]
	ds_read_b128 v[0:3], v202 offset:32768
	ds_read_b128 v[4:7], v202 offset:40960
	s_waitcnt lgkmcnt(1)
	v_mfma_f32_32x32x16_bf16 v[32:47], v[0:3], v[112:115], v[32:47]
	v_bitop3_b32 v0, v176, v62, s45 bitop3:0x36
	v_add_u32_e32 v203, v61, v0
	s_waitcnt lgkmcnt(0)
	v_mfma_f32_32x32x16_bf16 v[16:31], v[4:7], v[112:115], v[16:31]
	ds_read_b128 v[0:3], v203 offset:32768
	ds_read_b128 v[4:7], v203 offset:40960
	s_waitcnt lgkmcnt(1)
	v_mfma_f32_32x32x16_bf16 v[32:47], v[0:3], v[108:111], v[32:47]
	v_bitop3_b32 v0, v176, v62, s46 bitop3:0x36
	v_add_u32_e32 v204, v61, v0
	s_waitcnt lgkmcnt(0)
	v_mfma_f32_32x32x16_bf16 v[16:31], v[4:7], v[108:111], v[16:31]
	ds_read_b128 v[0:3], v204 offset:32768
	ds_read_b128 v[4:7], v204 offset:40960
	s_waitcnt lgkmcnt(1)
	v_mfma_f32_32x32x16_bf16 v[32:47], v[0:3], v[104:107], v[32:47]
	v_bitop3_b32 v0, v176, v62, s42 bitop3:0x36
	v_add_u32_e32 v205, v61, v0
	ds_read_b128 v[50:53], v205 offset:32768
	ds_read_b128 v[54:57], v205 offset:40960
	s_waitcnt lgkmcnt(1)
; #define SBAR() __builtin_amdgcn_sched_barrier(0)
; #define SLOAD(i, k0) do { sr_[i].vs0 = *reinterpret_cast<const bf16x8*>(vptr + (size_t)((k0) + sr) * vstr); \
;     sr_[i].vs1 = *reinterpret_cast<const bf16x8*>(vptr + (size_t)((k0) + 32 + sr) * vstr); \
;     sr_[i].ks0 = *reinterpret_cast<const bf16x8*>(kptr + (size_t)((k0) + sr) * kstr); \
;     sr_[i].ks1 = *reinterpret_cast<const bf16x8*>(kptr + (size_t)((k0) + 32 + sr) * kstr); } while (0)
; #define SWRITE(b, i) do { *(LAS bf16x8*)(V_lds + (b) * SHM_V + vst0) = sr_[i].vs0;          \
;     *(LAS bf16x8*)(V_lds + (b) * SHM_V + vst1) = sr_[i].vs1; const int kc = sc * 2;               \
;     *(LAS bf16x8*)(K_lds + (b) * SHM_K + KSWZ(sr, kc)) = sr_[i].ks0;                       \
;     *(LAS bf16x8*)(K_lds + (b) * SHM_K + KSWZ(32 + sr, kc)) = sr_[i].ks1; } while (0)
; #define SWAIT() asm volatile("s_waitcnt vmcnt(4)" ::: "memory")
; template <int NDQ, int NDV> ...
;     ...
;   qkt<NDQ>(pA0, pA1, K_lds, qr, r32, hi); partialSM(pA0, pA1, m_reg, mnA, alA, Cs, thr);
;   SLOAD(SO, 64); if (2 < NT) SLOAD(SE, 128);
;   SWAIT(); SWRITE(1, SO); __syncthreads();
;   for (int j = 1; j + 1 < NT; j += 2) {
;     SBAR(); qkt<NDQ>(pB0, pB1, K_lds + SHM_K, qr, r32, hi);
	v_mfma_f32_32x32x16_bf16 v[32:47], v[50:53], v[100:103], v[32:47]
	v_bitop3_b32 v50, v176, v62, s47 bitop3:0x36
	v_add_u32_e32 v206, v61, v50
	ds_read_b128 v[50:53], v206 offset:32768
	v_add_u32_e32 v61, 64, v70
	v_mfma_f32_32x32x16_bf16 v[16:31], v[4:7], v[104:107], v[16:31]
	v_mov_b64_e32 v[0:1], s[12:13]
	v_mov_b64_e32 v[14:15], s[26:27]
	v_mov_b64_e32 v[2:3], s[14:15]
	v_mov_b64_e32 v[4:5], s[16:17]
	v_mov_b64_e32 v[6:7], s[18:19]
	v_mov_b64_e32 v[8:9], s[20:21]
	v_mov_b64_e32 v[10:11], s[22:23]
	s_waitcnt lgkmcnt(1)
	v_mfma_f32_32x32x16_bf16 v[16:31], v[54:57], v[100:103], v[16:31]
	ds_read_b128 v[54:57], v206 offset:40960
	v_mov_b64_e32 v[12:13], s[24:25]
	s_waitcnt lgkmcnt(1)
	v_mfma_f32_32x32x16_bf16 v[32:47], v[50:53], v[96:99], v[32:47]
	v_and_or_b32 v50, v59, 24, v60
	v_and_b32_e32 v51, 0x100, v59
	v_or3_b32 v72, v50, v58, v51
	v_mad_i64_i32 v[58:59], s[0:1], v61, s40, v[48:49]
	global_load_dwordx4 v[50:53], v[58:59], off offset:2560
	v_add_u32_e32 v194, 0, v72
	s_waitcnt lgkmcnt(0)
	v_mfma_f32_32x32x16_bf16 v[16:31], v[54:57], v[96:99], v[16:31]
	s_nop 3
	v_max_f32_e32 v54, v33, v33
	v_max_f32_e32 v55, v32, v32
	v_max_f32_e32 v54, v55, v54
	v_max3_f32 v54, v54, v34, v35
	v_max3_f32 v54, v54, v36, v37
	v_max3_f32 v54, v54, v38, v39
	v_max3_f32 v54, v54, v40, v41
	v_max3_f32 v54, v54, v42, v43
	v_max3_f32 v54, v54, v44, v45
	v_max3_f32 v54, v54, v46, v47
	v_max3_f32 v68, v54, v16, v17
	v_max3_f32 v68, v68, v18, v19
	v_max3_f32 v68, v68, v20, v21
	v_max3_f32 v68, v68, v22, v23
	v_max3_f32 v68, v68, v24, v25
	v_max3_f32 v68, v68, v26, v27
	v_add_u32_e32 v54, 0x60, v70
	v_max3_f32 v73, v68, v28, v29
	v_add_u32_e32 v68, 0xa0, v70
	v_mad_i64_i32 v[62:63], s[0:1], v54, s40, v[48:49]
	v_mad_i64_i32 v[68:69], s[0:1], v68, s40, v[48:49]
	v_add_u32_e32 v70, 0x80, v70
	global_load_dwordx4 v[54:57], v[62:63], off offset:2560
	s_nop 0
	global_load_dwordx4 v[58:61], v[58:59], off offset:2048
	s_nop 0
	global_load_dwordx4 v[62:65], v[62:63], off offset:2048
	v_mad_i64_i32 v[48:49], s[0:1], v70, s40, v[48:49]
	global_load_dwordx4 v[132:135], v[68:69], off offset:2048
	global_load_dwordx4 v[136:139], v[68:69], off offset:2560
	global_load_dwordx4 v[140:143], v[48:49], off offset:2048
	global_load_dwordx4 v[128:131], v[48:49], off offset:2560
	v_max3_f32 v48, v73, v30, v31
	v_mov_b32_e32 v49, v48
	s_nop 1
	v_permlane32_swap_b32_e32 v48, v49
	v_max_f32_e32 v49, v49, v49
	v_max_f32_e32 v48, v48, v48
	v_max_f32_e32 v48, v48, v49
	v_add_f32_e32 v49, 0x7149f2ca, v48
	v_max_f32_e32 v48, 0xf149f2ca, v48
	v_cmp_ge_f32_e32 vcc, s48, v49
	v_sub_f32_e32 v49, 0xf149f2ca, v48
	v_mul_f32_e32 v49, 0x3e0293ee, v49
	v_exp_f32_e32 v49, v49
	s_cmp_eq_u64 vcc, exec
	s_cselect_b64 vcc, -1, 0
	v_cndmask_b32_e32 v160, v48, v186, vcc
	v_mul_f32_e32 v48, 0xbe0293ee, v160
	v_cndmask_b32_e64 v207, v49, 1.0, vcc
	v_mov_b32_e32 v49, v48
	v_fmamk_f32 v32, v32, 0x3e0293ee, v48
	v_fmamk_f32 v33, v33, 0x3e0293ee, v48
	v_fmamk_f32 v34, v34, 0x3e0293ee, v48
	v_fmamk_f32 v35, v35, 0x3e0293ee, v48
	v_fmamk_f32 v36, v36, 0x3e0293ee, v48
	v_fmamk_f32 v37, v37, 0x3e0293ee, v48
	v_fmamk_f32 v38, v38, 0x3e0293ee, v48
	v_fmamk_f32 v39, v39, 0x3e0293ee, v48
	v_fmamk_f32 v40, v40, 0x3e0293ee, v48
	v_fmamk_f32 v41, v41, 0x3e0293ee, v48
	v_fmamk_f32 v42, v42, 0x3e0293ee, v48
	v_fmamk_f32 v43, v43, 0x3e0293ee, v48
	v_fmamk_f32 v44, v44, 0x3e0293ee, v48
	v_fmamk_f32 v45, v45, 0x3e0293ee, v48
	v_fmamk_f32 v46, v46, 0x3e0293ee, v48
	v_fmac_f32_e32 v49, 0x3e0293ee, v47
	v_pk_fma_f32 v[154:155], v[16:17], s[4:5], v[48:49] op_sel_hi:[1,0,0]
	v_exp_f32_e32 v175, v32
	v_exp_f32_e32 v214, v33
	v_exp_f32_e32 v173, v34
	v_exp_f32_e32 v211, v35
	v_exp_f32_e32 v172, v36
	v_exp_f32_e32 v174, v37
	v_exp_f32_e32 v170, v38
	v_exp_f32_e32 v171, v39
	v_exp_f32_e32 v167, v40
	v_exp_f32_e32 v169, v41
	v_exp_f32_e32 v166, v42
	v_exp_f32_e32 v168, v43
	v_exp_f32_e32 v163, v44
	v_exp_f32_e32 v165, v45
	v_exp_f32_e32 v162, v46
	v_exp_f32_e32 v164, v49
	v_mad_i64_i32 v[16:17], s[30:31], s3, v187, v[66:67]
	s_waitcnt vmcnt(4)
	v_lshl_or_b32 v16, s2, 6, v16
	v_pk_fma_f32 v[150:151], v[30:31], s[4:5], v[48:49] op_sel_hi:[1,0,0]
	v_pk_fma_f32 v[156:157], v[28:29], s[4:5], v[48:49] op_sel_hi:[1,0,0]
	v_pk_fma_f32 v[158:159], v[26:27], s[4:5], v[48:49] op_sel_hi:[1,0,0]
	v_pk_fma_f32 v[144:145], v[24:25], s[4:5], v[48:49] op_sel_hi:[1,0,0]
	v_pk_fma_f32 v[146:147], v[22:23], s[4:5], v[48:49] op_sel_hi:[1,0,0]
	v_pk_fma_f32 v[148:149], v[20:21], s[4:5], v[48:49] op_sel_hi:[1,0,0]
	v_pk_fma_f32 v[152:153], v[18:19], s[4:5], v[48:49] op_sel_hi:[1,0,0]
	s_waitcnt vmcnt(7)
	ds_write_b128 v197, v[50:53] offset:16384
	s_waitcnt vmcnt(6)
	ds_write_b128 v198, v[54:57] offset:16384
	s_waitcnt vmcnt(5)
	ds_write_b128 v195, v[58:61] offset:49152
	s_waitcnt vmcnt(4)
	ds_write_b128 v196, v[62:65] offset:49152
	v_lshl_add_u64 v[184:185], v[178:179], 0, v[16:17]
	v_mov_b64_e32 v[62:63], v[14:15]
	v_mov_b64_e32 v[46:47], v[14:15]
	v_mov_b64_e32 v[30:31], v[14:15]
	v_cmp_gt_u32_e64 s[0:1], 32, v71
	v_add_u32_e32 v193, s75, v72
	v_mov_b64_e32 v[60:61], v[12:13]
	v_mov_b64_e32 v[58:59], v[10:11]
	v_mov_b64_e32 v[56:57], v[8:9]
	v_mov_b64_e32 v[54:55], v[6:7]
	v_mov_b64_e32 v[52:53], v[4:5]
	v_mov_b64_e32 v[50:51], v[2:3]
	v_mov_b64_e32 v[48:49], v[0:1]
	v_mov_b64_e32 v[44:45], v[12:13]
	v_mov_b64_e32 v[42:43], v[10:11]
	v_mov_b64_e32 v[40:41], v[8:9]
	v_mov_b64_e32 v[38:39], v[6:7]
	v_mov_b64_e32 v[36:37], v[4:5]
	v_mov_b64_e32 v[34:35], v[2:3]
	v_mov_b64_e32 v[32:33], v[0:1]
	v_mov_b64_e32 v[28:29], v[12:13]
	v_mov_b64_e32 v[26:27], v[10:11]
	v_mov_b64_e32 v[24:25], v[8:9]
	v_mov_b64_e32 v[22:23], v[6:7]
	v_mov_b64_e32 v[20:21], v[4:5]
	v_mov_b64_e32 v[18:19], v[2:3]
	v_mov_b64_e32 v[16:17], v[0:1]
	v_mov_b32_e32 v236, v175
	v_mov_b32_e32 v237, v214
	v_mov_b32_e32 v238, v173
	v_mov_b32_e32 v239, v211
	v_mov_b32_e32 v240, v172
	v_mov_b32_e32 v241, v174
	v_mov_b32_e32 v242, v170
	v_mov_b32_e32 v243, v171
	v_mov_b32_e32 v244, v167
	v_mov_b32_e32 v245, v169
	v_mov_b32_e32 v246, v166
	v_mov_b32_e32 v247, v168
	v_mov_b32_e32 v248, v163
	v_mov_b32_e32 v249, v165
	v_mov_b32_e32 v250, v162
	v_mov_b32_e32 v251, v164
	s_waitcnt lgkmcnt(0)
	s_barrier
	ds_read_b128 v[224:227], v199 offset:49152
	ds_read_b128 v[228:231], v199 offset:57344
	ds_read_b128 v[216:219], v200 offset:49152
	ds_read_b128 v[220:223], v200 offset:57344
; #define LAS __attribute__((address_space(3)))
; __device__ __forceinline__ void finishSM(f32x16& p0, f32x16& p1, float alpha, float& l_reg, bf16x8& pa0, bf16x8& pa1, bf16x8& pa2, bf16x8& pa3) {
; #pragma unroll
;   for (int r = 0; r < 16; ++r) p1[r] = __builtin_amdgcn_exp2f(p1[r]);
;   float ps = 0;
; #pragma unroll
;   for (int r = 0; r < 16; ++r) ps += p0[r];
; #pragma unroll
;   for (int r = 0; r < 16; ++r) ps += p1[r];
;   { auto rr = __builtin_amdgcn_permlane32_swap(__float_as_uint(ps), __float_as_uint(ps), false, false);
;     ps = __uint_as_float(rr[0]) + __uint_as_float(rr[1]); }
;   l_reg = l_reg * alpha + ps;
;     ...
;   PK4(p0, 0, pa0); PK4(p0, 8, pa1); PK4(p1, 0, pa2); PK4(p1, 8, pa3);
;     ...
; }
; template <int NDQ>
; __device__ __forceinline__ void qkt(f32x16& p0, f32x16& p1, const LAS char* Ks, const bf16x8* qr, int r32, int hi) {
;   p0 = f32x16{}; p1 = f32x16{};
; #pragma unroll
;   for (int d0 = 0; d0 < NDQ; ++d0) { const int cb = (d0 * 16 + hi * 8) * 2;
;     bf16x8 b0 = *reinterpret_cast<const LAS bf16x8*>(Ks + KSWZ(r32, cb));
;     bf16x8 b1 = *reinterpret_cast<const LAS bf16x8*>(Ks + KSWZ(32 + r32, cb));
;     p0 = __builtin_amdgcn_mfma_f32_32x32x16_bf16(b0, qr[d0], p0, 0, 0, 0);
;     p1 = __builtin_amdgcn_mfma_f32_32x32x16_bf16(b1, qr[d0], p1, 0, 0, 0); }
; }
.LBB0_2123:
	v_add_f32_e32 v161, 0, v236
	v_add_f32_e32 v161, v237, v161
	s_waitcnt lgkmcnt(3)
	v_mfma_f32_32x32x16_bf16 v[80:95], v[224:227], v[124:127], 0
	v_add_f32_e32 v161, v238, v161
	v_add_f32_e32 v161, v239, v161
	v_add_f32_e32 v161, v240, v161
	v_add_f32_e32 v161, v241, v161
	v_add_f32_e32 v161, v242, v161
	v_add_f32_e32 v161, v243, v161
	s_waitcnt lgkmcnt(2)
	v_mfma_f32_32x32x16_bf16 v[64:79], v[228:231], v[124:127], 0
	v_add_f32_e32 v161, v244, v161
	v_add_f32_e32 v161, v245, v161
	v_add_f32_e32 v161, v246, v161
	v_add_f32_e32 v161, v247, v161
	v_exp_f32_e32 v154, v154
	s_waitcnt lgkmcnt(1)
	v_mfma_f32_32x32x16_bf16 v[80:95], v[216:219], v[120:123], v[80:95]
	v_add_f32_e32 v161, v248, v161
	v_exp_f32_e32 v155, v155
	v_add_f32_e32 v161, v249, v161
	v_exp_f32_e32 v152, v152
	s_waitcnt lgkmcnt(0)
	v_mfma_f32_32x32x16_bf16 v[64:79], v[220:223], v[120:123], v[64:79]
	ds_read_b128 v[216:219], v201 offset:49152
	ds_read_b128 v[220:223], v201 offset:57344
	v_add_f32_e32 v161, v250, v161
	v_exp_f32_e32 v153, v153
	v_add_f32_e32 v161, v251, v161
	v_exp_f32_e32 v148, v148
	s_waitcnt lgkmcnt(1)
	v_mfma_f32_32x32x16_bf16 v[80:95], v[216:219], v[116:119], v[80:95]
	v_add_f32_e32 v161, v154, v161
	v_exp_f32_e32 v149, v149
	v_add_f32_e32 v161, v155, v161
	v_exp_f32_e32 v146, v146
	s_waitcnt lgkmcnt(0)
	v_mfma_f32_32x32x16_bf16 v[64:79], v[220:223], v[116:119], v[64:79]
	ds_read_b128 v[216:219], v202 offset:49152
	ds_read_b128 v[220:223], v202 offset:57344
	v_add_f32_e32 v161, v152, v161
	v_exp_f32_e32 v147, v147
	v_add_f32_e32 v161, v153, v161
	v_exp_f32_e32 v144, v144
	s_waitcnt lgkmcnt(1)
	v_mfma_f32_32x32x16_bf16 v[80:95], v[216:219], v[112:115], v[80:95]
	v_add_f32_e32 v161, v148, v161
	v_exp_f32_e32 v145, v145
	v_add_f32_e32 v161, v149, v161
	v_exp_f32_e32 v158, v158
	s_waitcnt lgkmcnt(0)
	v_mfma_f32_32x32x16_bf16 v[64:79], v[220:223], v[112:115], v[64:79]
	ds_read_b128 v[216:219], v203 offset:49152
	ds_read_b128 v[220:223], v203 offset:57344
	v_add_f32_e32 v161, v146, v161
	v_exp_f32_e32 v159, v159
	v_add_f32_e32 v161, v147, v161
	v_exp_f32_e32 v156, v156
	s_waitcnt lgkmcnt(1)
	v_mfma_f32_32x32x16_bf16 v[80:95], v[216:219], v[108:111], v[80:95]
	v_add_f32_e32 v161, v144, v161
	v_exp_f32_e32 v157, v157
	v_add_f32_e32 v161, v145, v161
	v_exp_f32_e32 v150, v150
	s_waitcnt lgkmcnt(0)
	v_mfma_f32_32x32x16_bf16 v[64:79], v[220:223], v[108:111], v[64:79]
	ds_read_b128 v[216:219], v204 offset:49152
	ds_read_b128 v[220:223], v204 offset:57344
	v_add_f32_e32 v161, v158, v161
	v_exp_f32_e32 v151, v151
	v_add_f32_e32 v161, v159, v161
	v_add_f32_e32 v161, v156, v161
	v_add_f32_e32 v161, v157, v161
	s_waitcnt lgkmcnt(1)
	v_mfma_f32_32x32x16_bf16 v[80:95], v[216:219], v[104:107], v[80:95]
	v_add_f32_e32 v161, v150, v161
	v_add_f32_e32 v208, v151, v161
	v_mov_b32_e32 v209, v208
	v_cvt_pk_bf16_f32 v210, v236, v237
	v_cvt_pk_bf16_f32 v211, v238, v239
	v_cvt_pk_bf16_f32 v212, v240, v241
	s_waitcnt lgkmcnt(0)
	v_mfma_f32_32x32x16_bf16 v[64:79], v[220:223], v[104:107], v[64:79]
	ds_read_b128 v[216:219], v205 offset:49152
	ds_read_b128 v[220:223], v205 offset:57344
	v_permlane32_swap_b32_e32 v208, v209
	v_cvt_pk_bf16_f32 v213, v242, v243
	v_cvt_pk_bf16_f32 v170, v244, v245
	v_cvt_pk_bf16_f32 v171, v246, v247
	v_permlane32_swap_b32_e32 v210, v212
	v_cvt_pk_bf16_f32 v172, v248, v249
	s_waitcnt lgkmcnt(1)
	v_mfma_f32_32x32x16_bf16 v[80:95], v[216:219], v[100:103], v[80:95]
	v_cvt_pk_bf16_f32 v173, v250, v251
	v_cvt_pk_bf16_f32 v162, v154, v155
	v_cvt_pk_bf16_f32 v163, v152, v153
	v_cvt_pk_bf16_f32 v164, v148, v149
	v_cvt_pk_bf16_f32 v165, v146, v147
	v_cvt_pk_bf16_f32 v166, v144, v145
	s_waitcnt lgkmcnt(0)
; #define SBAR() __builtin_amdgcn_sched_barrier(0)
; #define SLOAD(i, k0) do { sr_[i].vs0 = *reinterpret_cast<const bf16x8*>(vptr + (size_t)((k0) + sr) * vstr); \
;     sr_[i].vs1 = *reinterpret_cast<const bf16x8*>(vptr + (size_t)((k0) + 32 + sr) * vstr); \
;     sr_[i].ks0 = *reinterpret_cast<const bf16x8*>(kptr + (size_t)((k0) + sr) * kstr); \
;     sr_[i].ks1 = *reinterpret_cast<const bf16x8*>(kptr + (size_t)((k0) + 32 + sr) * kstr); } while (0)
; __device__ __forceinline__ int v_st(int k, int c) { const int kk = (k & ~0xC) | ((k & 4) << 1) | ((k & 8) >> 1); return ((kk >> 3) * 4 + (c >> 5)) * 512 + ((kk & 7) * 32 + (c & 31)) * 2; }
; __device__ __forceinline__ int v_rd_base(int lane) { return ((lane & 3) << 3) | (((lane >> 2) & 3) << 6) | (((lane >> 4) & 1) << 5) | (((lane >> 5) & 1) << 8); }
; template <int OFF> __device__ __forceinline__ s16x4 tr_read(int vb) {
;   s16x4 r; asm volatile("ds_read_b64_tr_b16 %0, %1 offset:%2" : "=&v"(r) : "v"(vb), "i"(OFF) : "memory"); return r;
; }
; template <int D0> __device__ __forceinline__ void pv_one(f32x16& od, int vb, bf16x8 pa0, bf16x8 pa1, bf16x8 pa2, bf16x8 pa3) {
;   const s16x4 l0 = tr_read<v_rd_off(D0, 0, 0)>(vb), h0 = tr_read<v_rd_off(D0, 0, 1)>(vb), l1 = tr_read<v_rd_off(D0, 1, 0)>(vb), h1 = tr_read<v_rd_off(D0, 1, 1)>(vb);
;   const s16x4 l2 = tr_read<v_rd_off(D0, 2, 0)>(vb), h2 = tr_read<v_rd_off(D0, 2, 1)>(vb), l3 = tr_read<v_rd_off(D0, 3, 0)>(vb), h3 = tr_read<v_rd_off(D0, 3, 1)>(vb);
;   asm volatile("s_waitcnt lgkmcnt(0)" ::: "memory"); SBAR();
;     ...
;   od = __builtin_amdgcn_mfma_f32_32x32x16_bf16(pa0, PK(l0, h0), od, 0, 0, 0);
;   od = __builtin_amdgcn_mfma_f32_32x32x16_bf16(pa1, PK(l1, h1), od, 0, 0, 0);
;   od = __builtin_amdgcn_mfma_f32_32x32x16_bf16(pa2, PK(l2, h2), od, 0, 0, 0);
;   od = __builtin_amdgcn_mfma_f32_32x32x16_bf16(pa3, PK(l3, h3), od, 0, 0, 0);
;     ...
; }
; template <int NDV>
; __device__ __forceinline__ void pv_d0(f32x16* o, int vb, bf16x8 pa0, bf16x8 pa1, bf16x8 pa2, bf16x8 pa3) {
;   pv_one<0>(o[0], vb, pa0, pa1, pa2, pa3); pv_one<1>(o[1], vb, pa0, pa1, pa2, pa3);
;   if constexpr (NDV == 4) { pv_one<2>(o[2], vb, pa0, pa1, pa2, pa3); pv_one<3>(o[3], vb, pa0, pa1, pa2, pa3); }
; }
; template <int NDQ, int NDV> ...
;     ...
;     SLOAD(SO, (j + 2) * 64); SBAR();
;     pv_d0<NDV>(o, vb0, pa0, pa1, pa2, pa3); partialSM(pB0, pB1, m_reg, mnB, alB, Cs, thr);
	v_mfma_f32_32x32x16_bf16 v[64:79], v[220:223], v[100:103], v[64:79]
	ds_read_b128 v[216:219], v206 offset:49152
	ds_read_b128 v[220:223], v206 offset:57344
	v_cvt_pk_bf16_f32 v167, v158, v159
	v_cvt_pk_bf16_f32 v168, v156, v157
	v_cvt_pk_bf16_f32 v169, v150, v151
	v_permlane32_swap_b32_e32 v211, v213
	v_permlane32_swap_b32_e32 v170, v172
	v_permlane32_swap_b32_e32 v171, v173
	s_waitcnt lgkmcnt(1)
	v_mfma_f32_32x32x16_bf16 v[80:95], v[216:219], v[96:99], v[80:95]
	v_permlane32_swap_b32_e32 v162, v164
	v_permlane32_swap_b32_e32 v163, v165
	v_permlane32_swap_b32_e32 v166, v168
	v_permlane32_swap_b32_e32 v167, v169
	s_waitcnt lgkmcnt(0)
	v_mfma_f32_32x32x16_bf16 v[64:79], v[220:223], v[96:99], v[64:79]
	v_add_co_u32_e32 v148, vcc, s50, v184
	s_nop 1
	v_addc_co_u32_e32 v149, vcc, -1, v185, vcc
	v_add_co_u32_e32 v152, vcc, s51, v184
	s_nop 1
	v_addc_co_u32_e32 v153, vcc, -1, v185, vcc
	global_load_dwordx4 v[144:147], v[148:149], off
	s_nop 0
	global_load_dwordx4 v[148:151], v[148:149], off offset:-512
	s_nop 0
	global_load_dwordx4 v[156:159], v[152:153], off
	s_nop 0
	global_load_dwordx4 v[152:155], v[152:153], off offset:-512
	s_waitcnt vmcnt(4)
	ds_write_b128 v195, v[140:143] offset:32768
	ds_write_b128 v196, v[132:135] offset:32768
	ds_read_b64_tr_b16 v[214:215], v194 offset:0
	ds_read_b64_tr_b16 v[216:217], v194 offset:0x800
	ds_read_b64_tr_b16 v[218:219], v194 offset:0x1000
	ds_read_b64_tr_b16 v[220:221], v194 offset:0x1800
	ds_read_b64_tr_b16 v[222:223], v194 offset:0x2000
	ds_read_b64_tr_b16 v[224:225], v194 offset:0x2800
	ds_read_b64_tr_b16 v[226:227], v194 offset:0x3000
	ds_read_b64_tr_b16 v[228:229], v194 offset:0x3800
	s_waitcnt lgkmcnt(6)
	v_mfma_f32_32x32x16_bf16 v[0:15], v[210:213], v[214:217], v[0:15]
	ds_read_b64_tr_b16 v[214:215], v194 offset:0x200
	ds_read_b64_tr_b16 v[216:217], v194 offset:0xa00
	v_max_f32_e32 v161, v80, v81
	v_max3_f32 v161, v161, v82, v83
	v_max3_f32 v161, v161, v84, v85
	v_max3_f32 v161, v161, v86, v87
	v_max3_f32 v161, v161, v88, v89
	v_max3_f32 v161, v161, v90, v91
	s_waitcnt lgkmcnt(6)
	v_mfma_f32_32x32x16_bf16 v[0:15], v[170:173], v[218:221], v[0:15]
	ds_read_b64_tr_b16 v[218:219], v194 offset:0x1200
	ds_read_b64_tr_b16 v[220:221], v194 offset:0x1a00
	v_max3_f32 v161, v161, v92, v93
	v_max3_f32 v161, v161, v94, v95
	v_max3_f32 v161, v161, v64, v65
	v_max3_f32 v161, v161, v66, v67
	v_max3_f32 v161, v161, v68, v69
	v_max3_f32 v161, v161, v70, v71
	s_waitcnt lgkmcnt(6)
	v_mfma_f32_32x32x16_bf16 v[0:15], v[162:165], v[222:225], v[0:15]
	ds_read_b64_tr_b16 v[222:223], v194 offset:0x2200
	ds_read_b64_tr_b16 v[224:225], v194 offset:0x2a00
	ds_read_b64_tr_b16 v[230:231], v194 offset:0x3200
	ds_read_b64_tr_b16 v[232:233], v194 offset:0x3a00
	v_max3_f32 v161, v161, v72, v73
	v_max3_f32 v161, v161, v74, v75
	v_max3_f32 v161, v161, v76, v77
	v_max3_f32 v161, v161, v78, v79
	v_mov_b32_e32 v174, v161
	s_nop 1
	s_waitcnt lgkmcnt(8)
	v_mfma_f32_32x32x16_bf16 v[0:15], v[166:169], v[226:229], v[0:15]
	v_permlane32_swap_b32_e32 v161, v174
	v_max_f32_e32 v161, v161, v174
	v_sub_f32_e32 v175, v161, v160
	v_max_f32_e32 v161, v160, v161
	v_cmp_ge_f32_e32 vcc, s48, v175
	s_cmp_eq_u64 vcc, exec
	s_waitcnt lgkmcnt(6)
	v_mfma_f32_32x32x16_bf16 v[48:63], v[210:213], v[214:217], v[48:63]
	ds_read_b64_tr_b16 v[214:215], v194 offset:0x400
	ds_read_b64_tr_b16 v[216:217], v194 offset:0xc00
	s_cselect_b64 s[2:3], -1, 0
	s_cbranch_scc0 .Lgqa_rareA

; #define LAS __attribute__((address_space(3)))
; #define SBAR() __builtin_amdgcn_sched_barrier(0)
; #define SLOAD(i, k0) do { sr_[i].vs0 = *reinterpret_cast<const bf16x8*>(vptr + (size_t)((k0) + sr) * vstr); \
;     sr_[i].vs1 = *reinterpret_cast<const bf16x8*>(vptr + (size_t)((k0) + 32 + sr) * vstr); \
;     sr_[i].ks0 = *reinterpret_cast<const bf16x8*>(kptr + (size_t)((k0) + sr) * kstr); \
;     sr_[i].ks1 = *reinterpret_cast<const bf16x8*>(kptr + (size_t)((k0) + 32 + sr) * kstr); } while (0)
; #define SWAIT() asm volatile("s_waitcnt vmcnt(4)" ::: "memory")
; #define RESC(a) do { if (__any((a) < 1.f)) { if (hi == 0) al_l[r32] = (a); asm volatile("s_waitcnt lgkmcnt(0)" ::: "memory"); \
;     _Pragma("unroll") for (int d = 0; d < NDV; ++d) _Pragma("unroll") for (int r = 0; r < 16; ++r) o[d][r] *= al_l[crow(r, hi)]; } } while (0)
; __device__ __forceinline__ void finishSM(f32x16& p0, f32x16& p1, float alpha, float& l_reg, bf16x8& pa0, bf16x8& pa1, bf16x8& pa2, bf16x8& pa3) {
; #pragma unroll
;   for (int r = 0; r < 16; ++r) p1[r] = __builtin_amdgcn_exp2f(p1[r]);
;   float ps = 0;
; #pragma unroll
;   for (int r = 0; r < 16; ++r) ps += p0[r];
; #pragma unroll
;   for (int r = 0; r < 16; ++r) ps += p1[r];
;   { auto rr = __builtin_amdgcn_permlane32_swap(__float_as_uint(ps), __float_as_uint(ps), false, false);
;     ps = __uint_as_float(rr[0]) + __uint_as_float(rr[1]); }
;   l_reg = l_reg * alpha + ps;
;     ...
;   PK4(p0, 0, pa0); PK4(p0, 8, pa1); PK4(p1, 0, pa2); PK4(p1, 8, pa3);
;     ...
; }
; template <int NDQ>
; __device__ __forceinline__ void qkt(f32x16& p0, f32x16& p1, const LAS char* Ks, const bf16x8* qr, int r32, int hi) {
;   p0 = f32x16{}; p1 = f32x16{};
; #pragma unroll
;   for (int d0 = 0; d0 < NDQ; ++d0) { const int cb = (d0 * 16 + hi * 8) * 2;
;     bf16x8 b0 = *reinterpret_cast<const LAS bf16x8*>(Ks + KSWZ(r32, cb));
;     bf16x8 b1 = *reinterpret_cast<const LAS bf16x8*>(Ks + KSWZ(32 + r32, cb));
;     p0 = __builtin_amdgcn_mfma_f32_32x32x16_bf16(b0, qr[d0], p0, 0, 0, 0);
;     p1 = __builtin_amdgcn_mfma_f32_32x32x16_bf16(b1, qr[d0], p1, 0, 0, 0); }
; }
; template <int NDQ, int NDV> ...
;     ...
;     __syncthreads(); SWAIT(); SWRITE(0, SE);
;     RESC(alB); __syncthreads();
;     SBAR(); qkt<NDQ>(pA0, pA1, K_lds, qr, r32, hi);
;     finishSM(pB0, pB1, alB, l_reg, pa0, pa1, pa2, pa3); SBAR();
;     if (j + 3 < NT) SLOAD(SE, (j + 3) * 64); SBAR();
.LBB0_2127:
	v_mov_b32_e32 v211, v234
	ds_read_b128 v[228:231], v200 offset:32768
	ds_read_b128 v[232:235], v200 offset:40960
	v_fmamk_f32 v221, v64, 0x3e0293ee, v175
	v_fmamk_f32 v222, v65, 0x3e0293ee, v175
	v_fmamk_f32 v223, v66, 0x3e0293ee, v175
	v_fmamk_f32 v224, v67, 0x3e0293ee, v175
	v_fmamk_f32 v225, v68, 0x3e0293ee, v175
	v_fmamk_f32 v214, v69, 0x3e0293ee, v175
	v_fmamk_f32 v215, v70, 0x3e0293ee, v175
	v_fmamk_f32 v216, v71, 0x3e0293ee, v175
	ds_read_b128 v[64:67], v199 offset:32768
	ds_read_b128 v[68:71], v199 offset:40960
	v_fmamk_f32 v217, v72, 0x3e0293ee, v175
	v_fmamk_f32 v218, v73, 0x3e0293ee, v175
	v_fmamk_f32 v219, v74, 0x3e0293ee, v175
	v_fmamk_f32 v220, v75, 0x3e0293ee, v175
	v_fmamk_f32 v213, v76, 0x3e0293ee, v175
	v_fmamk_f32 v226, v77, 0x3e0293ee, v175
	v_fmamk_f32 v227, v78, 0x3e0293ee, v175
	v_fmamk_f32 v212, v79, 0x3e0293ee, v175
	s_add_i32 s61, s61, 2
	v_exp_f32_e32 v221, v221
	s_waitcnt lgkmcnt(1)
	v_mfma_f32_32x32x16_bf16 v[80:95], v[64:67], v[124:127], 0
	v_exp_f32_e32 v222, v222
	v_exp_f32_e32 v223, v223
	v_exp_f32_e32 v224, v224
	s_waitcnt lgkmcnt(0)
	v_mfma_f32_32x32x16_bf16 v[64:79], v[68:71], v[124:127], 0
	v_exp_f32_e32 v225, v225
	v_exp_f32_e32 v214, v214
	v_exp_f32_e32 v215, v215
	v_mfma_f32_32x32x16_bf16 v[80:95], v[228:231], v[120:123], v[80:95]
	v_exp_f32_e32 v216, v216
	v_exp_f32_e32 v217, v217
	v_exp_f32_e32 v218, v218
	v_mfma_f32_32x32x16_bf16 v[64:79], v[232:235], v[120:123], v[64:79]
	ds_read_b128 v[228:231], v201 offset:32768
	ds_read_b128 v[232:235], v201 offset:40960
	v_exp_f32_e32 v219, v219
	v_exp_f32_e32 v220, v220
	v_exp_f32_e32 v226, v226
	s_waitcnt lgkmcnt(1)
	v_mfma_f32_32x32x16_bf16 v[80:95], v[228:231], v[116:119], v[80:95]
	v_exp_f32_e32 v227, v227
	v_exp_f32_e32 v253, v212
	v_exp_f32_e32 v252, v213
	s_waitcnt lgkmcnt(0)
	v_mfma_f32_32x32x16_bf16 v[64:79], v[232:235], v[116:119], v[64:79]
	ds_read_b128 v[228:231], v202 offset:32768
	ds_read_b128 v[232:235], v202 offset:40960
	v_add_f32_e32 v212, 0, v236
	v_add_f32_e32 v212, v237, v212
	v_add_f32_e32 v212, v238, v212
	v_add_f32_e32 v212, v239, v212
	v_add_f32_e32 v212, v240, v212
	v_add_f32_e32 v212, v241, v212
	s_waitcnt lgkmcnt(1)
	v_mfma_f32_32x32x16_bf16 v[80:95], v[228:231], v[112:115], v[80:95]
	v_add_f32_e32 v212, v242, v212
	v_add_f32_e32 v212, v243, v212
	v_add_f32_e32 v212, v244, v212
	v_add_f32_e32 v212, v245, v212
	v_add_f32_e32 v212, v246, v212
	v_add_f32_e32 v212, v247, v212
	s_waitcnt lgkmcnt(0)
	v_mfma_f32_32x32x16_bf16 v[64:79], v[232:235], v[112:115], v[64:79]
	ds_read_b128 v[228:231], v203 offset:32768
	ds_read_b128 v[232:235], v203 offset:40960
	v_add_f32_e32 v212, v248, v212
	v_add_f32_e32 v212, v249, v212
	v_add_f32_e32 v212, v250, v212
	v_add_f32_e32 v212, v251, v212
	v_add_f32_e32 v212, v221, v212
	v_add_f32_e32 v212, v222, v212
	s_waitcnt lgkmcnt(1)
	v_mfma_f32_32x32x16_bf16 v[80:95], v[228:231], v[108:111], v[80:95]
	v_add_f32_e32 v212, v223, v212
	v_add_f32_e32 v212, v224, v212
	v_add_f32_e32 v212, v225, v212
	v_add_f32_e32 v212, v214, v212
	v_add_f32_e32 v212, v215, v212
	v_add_f32_e32 v212, v216, v212
	s_waitcnt lgkmcnt(0)
	v_mfma_f32_32x32x16_bf16 v[64:79], v[232:235], v[108:111], v[64:79]
	ds_read_b128 v[228:231], v204 offset:32768
	ds_read_b128 v[232:235], v204 offset:40960
	v_add_f32_e32 v212, v217, v212
	v_add_f32_e32 v212, v218, v212
	v_add_f32_e32 v212, v219, v212
	v_add_f32_e32 v212, v220, v212
	v_add_f32_e32 v212, v252, v212
	v_add_f32_e32 v212, v226, v212
	s_waitcnt lgkmcnt(1)
	v_mfma_f32_32x32x16_bf16 v[80:95], v[228:231], v[104:107], v[80:95]
	v_add_f32_e32 v212, v227, v212
	v_add_f32_e32 v212, v253, v212
	v_mov_b32_e32 v213, v212
	v_cvt_pk_bf16_f32 v160, v236, v237
	v_cvt_pk_bf16_f32 v161, v238, v239
	v_cvt_pk_bf16_f32 v162, v240, v241
	s_waitcnt lgkmcnt(0)
	v_mfma_f32_32x32x16_bf16 v[64:79], v[232:235], v[104:107], v[64:79]
	ds_read_b128 v[228:231], v205 offset:32768
	ds_read_b128 v[232:235], v205 offset:40960
	v_cvt_pk_bf16_f32 v163, v242, v243
	v_cvt_pk_bf16_f32 v164, v244, v245
	v_cvt_pk_bf16_f32 v165, v246, v247
	v_cvt_pk_bf16_f32 v166, v248, v249
	v_cvt_pk_bf16_f32 v167, v250, v251
	v_cvt_pk_bf16_f32 v168, v221, v222
	s_waitcnt lgkmcnt(1)
	v_mfma_f32_32x32x16_bf16 v[80:95], v[228:231], v[100:103], v[80:95]
	v_cvt_pk_bf16_f32 v169, v223, v224
	v_cvt_pk_bf16_f32 v170, v225, v214
	v_cvt_pk_bf16_f32 v171, v215, v216
	v_cvt_pk_bf16_f32 v172, v217, v218
	v_cvt_pk_bf16_f32 v173, v219, v220
	v_cvt_pk_bf16_f32 v174, v252, v226
	s_waitcnt lgkmcnt(0)
	v_mfma_f32_32x32x16_bf16 v[64:79], v[232:235], v[100:103], v[64:79]
	ds_read_b128 v[228:231], v206 offset:32768
	ds_read_b128 v[232:235], v206 offset:40960
	v_cvt_pk_bf16_f32 v175, v227, v253
	v_permlane32_swap_b32_e32 v212, v213
	v_permlane32_swap_b32_e32 v160, v162
	v_permlane32_swap_b32_e32 v161, v163
	v_permlane32_swap_b32_e32 v164, v166
	v_permlane32_swap_b32_e32 v165, v167
	s_waitcnt lgkmcnt(1)
	v_mfma_f32_32x32x16_bf16 v[80:95], v[228:231], v[96:99], v[80:95]
	v_permlane32_swap_b32_e32 v168, v170
	v_permlane32_swap_b32_e32 v169, v171
	v_permlane32_swap_b32_e32 v172, v174
	v_permlane32_swap_b32_e32 v173, v175
	s_waitcnt lgkmcnt(0)
	v_mfma_f32_32x32x16_bf16 v[64:79], v[232:235], v[96:99], v[64:79]
	s_cmpk_gt_u32 s61, 0x80
	s_cselect_b64 s[30:31], -1, 0
	s_and_b64 vcc, exec, s[30:31]
	s_cbranch_vccnz .LBB0_2129
	v_add_co_u32_e32 v132, vcc, 0xfffe8000, v184
	s_nop 1
	v_addc_co_u32_e32 v133, vcc, -1, v185, vcc
	global_load_dwordx4 v[128:131], v[132:133], off
	global_load_dwordx4 v[140:143], v[132:133], off offset:-512
	global_load_dwordx4 v[136:139], v[184:185], off
	s_nop 0
	global_load_dwordx4 v[132:135], v[184:185], off offset:-512

; #define SBAR() __builtin_amdgcn_sched_barrier(0)
; #define SLOAD(i, k0) do { sr_[i].vs0 = *reinterpret_cast<const bf16x8*>(vptr + (size_t)((k0) + sr) * vstr); \
;     sr_[i].vs1 = *reinterpret_cast<const bf16x8*>(vptr + (size_t)((k0) + 32 + sr) * vstr); \
;     sr_[i].ks0 = *reinterpret_cast<const bf16x8*>(kptr + (size_t)((k0) + sr) * kstr); \
;     sr_[i].ks1 = *reinterpret_cast<const bf16x8*>(kptr + (size_t)((k0) + 32 + sr) * kstr); } while (0)
; #define SWRITE(b, i) do { *(LAS bf16x8*)(V_lds + (b) * SHM_V + vst0) = sr_[i].vs0;          \
;     *(LAS bf16x8*)(V_lds + (b) * SHM_V + vst1) = sr_[i].vs1; const int kc = sc * 2;               \
;     *(LAS bf16x8*)(K_lds + (b) * SHM_K + KSWZ(sr, kc)) = sr_[i].ks0;                       \
;     *(LAS bf16x8*)(K_lds + (b) * SHM_K + KSWZ(32 + sr, kc)) = sr_[i].ks1; } while (0)
; #define SWAIT() asm volatile("s_waitcnt vmcnt(4)" ::: "memory")
; #define RESC(a) do { if (__any((a) < 1.f)) { if (hi == 0) al_l[r32] = (a); asm volatile("s_waitcnt lgkmcnt(0)" ::: "memory"); \
;     _Pragma("unroll") for (int d = 0; d < NDV; ++d) _Pragma("unroll") for (int r = 0; r < 16; ++r) o[d][r] *= al_l[crow(r, hi)]; } } while (0)
; __device__ __forceinline__ void partialSM(f32x16& p0, f32x16& p1, float& m_reg, float& mn, float& alpha, float C, float thr) {
;     ...
;   for (int r = 0; r < 16; ++r) p0[r] = fmaf(p0[r], C, mnC);
; #pragma unroll
;   for (int r = 0; r < 16; ++r) p1[r] = fmaf(p1[r], C, mnC);
; template <int NDQ, int NDV> ...
;     ...
;   for (int j = 1; j + 1 < NT; j += 2) {
;     SBAR(); qkt<NDQ>(pB0, pB1, K_lds + SHM_K, qr, r32, hi);
;     finishSM(pA0, pA1, alA, l_reg, pa0, pa1, pa2, pa3); SBAR();
;     SLOAD(SO, (j + 2) * 64); SBAR();
;     pv_d0<NDV>(o, vb0, pa0, pa1, pa2, pa3); partialSM(pB0, pB1, m_reg, mnB, alB, Cs, thr);
;     __syncthreads(); SWAIT(); SWRITE(0, SE);
;     RESC(alB); __syncthreads();
;     SBAR(); qkt<NDQ>(pA0, pA1, K_lds, qr, r32, hi);
;     finishSM(pB0, pB1, alB, l_reg, pa0, pa1, pa2, pa3); SBAR();
;     if (j + 3 < NT) SLOAD(SE, (j + 3) * 64); SBAR();
;     pv_d0<NDV>(o, vb0 + SHM_V, pa0, pa1, pa2, pa3); partialSM(pA0, pA1, m_reg, mnA, alA, Cs, thr);
;     __syncthreads(); SWAIT(); SWRITE(1, SO);
;     RESC(alA); __syncthreads();
;   }
.LBB0_2133:
	ds_read_b128 v[224:227], v199 offset:49152
	ds_read_b128 v[228:231], v199 offset:57344
	ds_read_b128 v[216:219], v200 offset:49152
	ds_read_b128 v[220:223], v200 offset:57344
	v_mov_b32_e32 v160, v234
	v_pk_fma_f32 v[154:155], v[64:65], s[4:5], v[252:253] op_sel_hi:[1,0,0]
	v_add_f32_e32 v64, v208, v209
	v_fmac_f32_e32 v64, v207, v192
	v_add_f32_e32 v192, v212, v213
	v_pk_fma_f32 v[152:153], v[66:67], s[4:5], v[252:253] op_sel_hi:[1,0,0]
	v_pk_fma_f32 v[148:149], v[68:69], s[4:5], v[252:253] op_sel_hi:[1,0,0]
	v_pk_fma_f32 v[146:147], v[70:71], s[4:5], v[252:253] op_sel_hi:[1,0,0]
	v_pk_fma_f32 v[144:145], v[72:73], s[4:5], v[252:253] op_sel_hi:[1,0,0]
	v_pk_fma_f32 v[158:159], v[74:75], s[4:5], v[252:253] op_sel_hi:[1,0,0]
	v_pk_fma_f32 v[156:157], v[76:77], s[4:5], v[252:253] op_sel_hi:[1,0,0]
	v_pk_fma_f32 v[150:151], v[78:79], s[4:5], v[252:253] op_sel_hi:[1,0,0]
	v_fmac_f32_e32 v192, v64, v210
	v_lshl_add_u64 v[184:185], v[184:185], 0, s[6:7]
	s_and_b64 vcc, exec, s[30:31]
	s_cbranch_vccnz .LBB0_2135
	v_mov_b32_e32 v207, v161
	s_branch .LBB0_2123
